# v28 + attention tail rebalance: context diff groups and context GQA items on different workgroups
# baseline (speedup 1.0000x reference)
.LBB0_486:
	v_readlane_b32 s16, v255, 19
	s_add_i32 s16, s16, s2
	s_cmpk_lg_i32 s2, 0x100
	s_cbranch_scc1 .Lattn_rb_orig
	s_cmpk_lt_i32 s16, 0xa00
	s_cbranch_scc1 .LBB0_487
	s_cmpk_lt_i32 s16, 0xa40
	s_cbranch_scc1 .Lattn_rb_up
	s_cmpk_lt_i32 s16, 0xb00
	s_cbranch_scc1 .LBB0_487
	s_cmpk_lt_i32 s16, 0xb40
	s_cbranch_scc1 .LBB0_659
	s_cmpk_lt_i32 s16, 0xb80
	s_cbranch_scc0 .LBB0_659
	s_addk_i32 s16, 0xfec0
	s_branch .LBB0_487
.Lattn_rb_up:
	s_addk_i32 s16, 0x100
	s_branch .LBB0_487
.Lattn_rb_orig:
	s_cmpk_lt_i32 s16, 0xb40
	s_cbranch_scc0 .LBB0_659
